# GEMM2 epilogue: counted per-group waits on the 16 residual loads instead of one vmcnt(0)
# baseline (speedup 1.0000x reference)
.LBB0_507:
	s_lshl_b32 s37, s44, 8
	v_mbcnt_lo_u32_b32 v205, -1, 0
	v_mbcnt_hi_u32_b32 v205, -1, v205
	s_add_i32 s37, s37, s60
	v_ashrrev_i32_e32 v214, 3, v205
	v_add_u32_e32 v104, s37, v214
	v_ashrrev_i32_e32 v105, 31, v104
	s_lshl_b32 s44, s10, 8
	v_lshlrev_b64 v[104:105], 10, v[104:105]
	s_ashr_i32 s45, s44, 31
	v_lshl_add_u64 v[196:197], v[104:105], 0, s[44:45]
	v_or_b32_e32 v104, s66, v196
	v_lshlrev_b32_e32 v105, 3, v205
	v_and_or_b32 v196, v105, 56, v104
	v_lshl_add_u64 v[104:105], v[196:197], 1, s[16:17]
	v_add_co_u32_e32 v106, vcc, s58, v104
	v_mul_lo_u32 v214, v214, s68
	s_nop 0
	v_addc_co_u32_e32 v107, vcc, 0, v105, vcc
	global_load_dwordx4 v[206:209], v[104:105], off nt
	global_load_dwordx4 v[210:213], v[106:107], off nt
	v_add_co_u32_e32 v106, vcc, s64, v104
	v_lshlrev_b32_e32 v205, 4, v205
	s_nop 0
	v_addc_co_u32_e32 v107, vcc, 0, v105, vcc
	v_add_co_u32_e32 v108, vcc, s71, v104
	v_add_u32_e32 v214, s67, v214
	s_nop 0
	v_addc_co_u32_e32 v109, vcc, 0, v105, vcc
	global_load_dwordx4 v[176:179], v[106:107], off nt
	global_load_dwordx4 v[180:183], v[108:109], off nt
	v_add_co_u32_e32 v106, vcc, s56, v104
	v_and_b32_e32 v205, 0x70, v205
	s_nop 0
	v_addc_co_u32_e32 v107, vcc, 0, v105, vcc
	v_add_co_u32_e32 v108, vcc, s57, v104
	v_add_u32_e32 v205, v214, v205
	s_nop 0
	v_addc_co_u32_e32 v109, vcc, 0, v105, vcc
	global_load_dwordx4 v[168:171], v[106:107], off nt
	global_load_dwordx4 v[172:175], v[108:109], off nt
	v_add_co_u32_e32 v106, vcc, s63, v104
	s_lshl_b32 s44, s10, 2
	s_nop 0
	v_addc_co_u32_e32 v107, vcc, 0, v105, vcc
	v_add_co_u32_e32 v108, vcc, s65, v104
	s_ashr_i32 s45, s44, 31
	s_nop 0
	v_addc_co_u32_e32 v109, vcc, 0, v105, vcc
	global_load_dwordx4 v[160:163], v[106:107], off nt
	global_load_dwordx4 v[164:167], v[108:109], off nt
	v_add_co_u32_e32 v106, vcc, s72, v104
	s_nop 1
	v_addc_co_u32_e32 v107, vcc, 0, v105, vcc
	v_add_co_u32_e32 v108, vcc, s73, v104
	s_nop 1
	v_addc_co_u32_e32 v109, vcc, 0, v105, vcc
	global_load_dwordx4 v[152:155], v[106:107], off nt
	global_load_dwordx4 v[156:159], v[108:109], off nt
	v_add_co_u32_e32 v106, vcc, s74, v104
	s_nop 1
	v_addc_co_u32_e32 v107, vcc, 0, v105, vcc
	v_add_co_u32_e32 v108, vcc, s75, v104
	s_nop 1
	v_addc_co_u32_e32 v109, vcc, 0, v105, vcc
	global_load_dwordx4 v[144:147], v[106:107], off nt
	global_load_dwordx4 v[148:151], v[108:109], off nt
	v_add_co_u32_e32 v106, vcc, s79, v104
	s_nop 1
	v_addc_co_u32_e32 v107, vcc, 0, v105, vcc
	v_add_co_u32_e32 v108, vcc, s80, v104
	s_nop 1
	v_addc_co_u32_e32 v109, vcc, 0, v105, vcc
	global_load_dwordx4 v[124:127], v[106:107], off nt
	global_load_dwordx4 v[128:131], v[108:109], off nt
	v_add_co_u32_e32 v106, vcc, s81, v104
	s_nop 1
	v_addc_co_u32_e32 v107, vcc, 0, v105, vcc
	v_add_co_u32_e32 v108, vcc, s82, v104
	s_nop 1
	v_addc_co_u32_e32 v109, vcc, 0, v105, vcc
	global_load_dwordx4 v[104:107], v[106:107], off nt
	s_nop 0
	global_load_dwordx4 v[108:111], v[108:109], off nt
	s_waitcnt vmcnt(14)
	ds_write_b128 v205, v[206:209]
	ds_write_b128 v205, v[210:213] offset:1152
	ds_read_b128 v[206:209], v204
	ds_read_b128 v[210:213], v204 offset:64
	s_waitcnt lgkmcnt(1)
	v_lshlrev_b32_e32 v214, 16, v206
	v_and_b32_e32 v206, 0xffff0000, v206
	v_add_f32_e32 v206, v141, v206
	v_lshlrev_b32_e32 v141, 16, v207
	v_add_f32_e32 v141, v142, v141
	v_and_b32_e32 v142, 0xffff0000, v207
	v_add_f32_e32 v143, v143, v142
	v_lshlrev_b32_e32 v142, 16, v208
	v_add_f32_e32 v142, v136, v142
	v_and_b32_e32 v136, 0xffff0000, v208
	v_add_f32_e32 v207, v137, v136
	v_lshlrev_b32_e32 v136, 16, v209
	v_add_f32_e32 v138, v138, v136
	v_and_b32_e32 v136, 0xffff0000, v209
	v_add_f32_e32 v209, v139, v136
	s_waitcnt lgkmcnt(0)
	v_lshlrev_b32_e32 v136, 16, v210
	v_add_f32_e32 v136, v132, v136
	v_and_b32_e32 v132, 0xffff0000, v210
	v_add_f32_e32 v137, v133, v132
	v_lshlrev_b32_e32 v132, 16, v211
	v_add_f32_e32 v134, v134, v132
	v_and_b32_e32 v132, 0xffff0000, v211
	v_add_f32_e32 v139, v135, v132
	v_lshlrev_b32_e32 v132, 16, v212
	v_add_f32_e32 v135, v120, v132
	v_and_b32_e32 v120, 0xffff0000, v212
	v_add_f32_e32 v208, v121, v120
	v_lshlrev_b32_e32 v120, 16, v213
	v_add_f32_e32 v122, v122, v120
	v_and_b32_e32 v120, 0xffff0000, v213
	v_add_f32_e32 v140, v140, v214
	v_add_f32_e32 v123, v123, v120
	v_mul_f32_e32 v120, v206, v206
	v_mul_f32_e32 v121, v143, v143
	v_fmac_f32_e32 v120, v140, v140
	v_fmac_f32_e32 v121, v141, v141
	v_add_f32_e32 v120, v120, v121
	v_mul_f32_e32 v121, v207, v207
	v_mul_f32_e32 v132, v209, v209
	v_fmac_f32_e32 v121, v142, v142
	v_fmac_f32_e32 v132, v138, v138
	v_add_f32_e32 v121, v121, v132
	v_add_f32_e32 v120, v120, v121
	v_mul_f32_e32 v121, v137, v137
	v_mul_f32_e32 v132, v139, v139
	v_fmac_f32_e32 v121, v136, v136
	v_fmac_f32_e32 v132, v134, v134
	v_add_f32_e32 v121, v121, v132
	v_mul_f32_e32 v132, v208, v208
	v_mul_f32_e32 v133, v123, v123
	v_fmac_f32_e32 v132, v135, v135
	v_fmac_f32_e32 v133, v122, v122
	v_add_f32_e32 v132, v132, v133
	v_add_f32_e32 v121, v121, v132
	v_and_b32_e32 v132, 64, v203
	v_add_f32_e32 v121, v120, v121
	v_add_u32_e32 v133, 64, v132
	v_mov_b32_e32 v210, v121
	s_nop 1
	v_permlane16_swap_b32_e32 v121, v210
	v_or_b32_e32 v120, s37, v198
	s_waitcnt lgkmcnt(0)
	v_add_f32_e32 v210, v121, v210
	v_xor_b32_e32 v121, 32, v203
	v_cmp_lt_i32_e32 vcc, v121, v133
	s_nop 1
	v_cndmask_b32_e32 v121, v203, v121, vcc
	v_lshlrev_b32_e32 v133, 2, v121
	v_mov_b32_e32 v211, v210
	s_nop 1
	v_permlane32_swap_b32_e32 v210, v211
	s_and_saveexec_b64 s[46:47], s[4:5]
	s_cbranch_execz .LBB0_509
	v_ashrrev_i32_e32 v121, 31, v120
	v_lshlrev_b64 v[212:213], 6, v[120:121]
	v_lshl_add_u64 v[212:213], s[18:19], 0, v[212:213]
	v_lshl_add_u64 v[212:213], s[44:45], 2, v[212:213]
	s_lshl_b32 s10, s59, 2
	v_lshl_add_u64 v[212:213], v[212:213], 0, s[10:11]
	s_waitcnt lgkmcnt(0)
	v_add_f32_e32 v121, v210, v211
	global_store_dword v[212:213], v121, off
.LBB0_509:
	s_or_b64 exec, exec, s[46:47]
	v_cvt_pk_bf16_f32 v140, v140, v206
	v_cvt_pk_bf16_f32 v141, v141, v143
	v_cvt_pk_bf16_f32 v142, v142, v207
	v_cvt_pk_bf16_f32 v143, v138, v209
	v_cvt_pk_bf16_f32 v136, v136, v137
	v_cvt_pk_bf16_f32 v137, v134, v139
	v_cvt_pk_bf16_f32 v138, v135, v208
	v_cvt_pk_bf16_f32 v139, v122, v123
	ds_write_b128 v204, v[140:143]
	ds_write_b128 v204, v[136:139] offset:64
	ds_read_b128 v[134:137], v205
	ds_read_b128 v[138:141], v205 offset:1152
	v_lshl_add_u64 v[122:123], v[196:197], 1, s[20:21]
	s_waitcnt lgkmcnt(1)
	global_store_dwordx4 v[122:123], v[134:137], off nt
	s_nop 1
	v_add_co_u32_e32 v134, vcc, s58, v122
	s_nop 1
	v_addc_co_u32_e32 v135, vcc, 0, v123, vcc
	s_waitcnt lgkmcnt(0)
	global_store_dwordx4 v[134:135], v[138:141], off nt
	s_waitcnt vmcnt(14)
	ds_write_b128 v205, v[176:179]
	ds_write_b128 v205, v[180:183] offset:1152
	ds_read_b128 v[134:137], v204
	ds_read_b128 v[138:141], v204 offset:64
	s_waitcnt lgkmcnt(1)
	v_lshlrev_b32_e32 v121, 16, v134
	v_add_f32_e32 v116, v116, v121
	v_and_b32_e32 v121, 0xffff0000, v134
	v_add_f32_e32 v121, v117, v121
	v_lshlrev_b32_e32 v117, 16, v135
	v_add_f32_e32 v117, v118, v117
	v_and_b32_e32 v118, 0xffff0000, v135
	v_add_f32_e32 v118, v119, v118
	v_lshlrev_b32_e32 v119, 16, v136
	v_add_f32_e32 v112, v112, v119
	v_and_b32_e32 v119, 0xffff0000, v136
	v_add_f32_e32 v119, v113, v119
	v_lshlrev_b32_e32 v113, 16, v137
	v_add_f32_e32 v114, v114, v113
	v_and_b32_e32 v113, 0xffff0000, v137
	v_add_f32_e32 v115, v115, v113
	s_waitcnt lgkmcnt(0)
	v_lshlrev_b32_e32 v113, 16, v138
	v_add_f32_e32 v100, v100, v113
	v_and_b32_e32 v113, 0xffff0000, v138
	v_add_f32_e32 v113, v101, v113
	v_lshlrev_b32_e32 v101, 16, v139
	v_add_f32_e32 v101, v102, v101
	v_and_b32_e32 v102, 0xffff0000, v139
	v_add_f32_e32 v102, v103, v102
	v_lshlrev_b32_e32 v103, 16, v140
	v_add_f32_e32 v96, v96, v103
	v_and_b32_e32 v103, 0xffff0000, v140
	v_add_f32_e32 v103, v97, v103
	v_lshlrev_b32_e32 v97, 16, v141
	v_add_f32_e32 v97, v98, v97
	v_and_b32_e32 v98, 0xffff0000, v141
	v_add_f32_e32 v98, v99, v98
	v_mul_f32_e32 v99, v121, v121
	v_mul_f32_e32 v134, v118, v118
	v_fmac_f32_e32 v99, v116, v116
	v_fmac_f32_e32 v134, v117, v117
	v_add_f32_e32 v99, v99, v134
	v_mul_f32_e32 v134, v119, v119
	v_mul_f32_e32 v135, v115, v115
	v_fmac_f32_e32 v134, v112, v112
	v_fmac_f32_e32 v135, v114, v114
	v_add_f32_e32 v134, v134, v135
	v_add_f32_e32 v99, v99, v134
	v_mul_f32_e32 v134, v113, v113
	v_mul_f32_e32 v135, v102, v102
	v_fmac_f32_e32 v134, v100, v100
	v_fmac_f32_e32 v135, v101, v101
	v_add_f32_e32 v134, v134, v135
	v_mul_f32_e32 v135, v103, v103
	v_mul_f32_e32 v136, v98, v98
	v_fmac_f32_e32 v135, v96, v96
	v_fmac_f32_e32 v136, v97, v97
	v_add_f32_e32 v135, v135, v136
	v_add_f32_e32 v134, v134, v135
	v_add_f32_e32 v99, v99, v134
	v_mov_b32_e32 v134, v99
	s_nop 1
	v_permlane16_swap_b32_e32 v99, v134
	s_waitcnt lgkmcnt(0)
	v_add_f32_e32 v99, v99, v134
	v_mov_b32_e32 v134, v99
	s_nop 1
	v_permlane32_swap_b32_e32 v99, v134
	s_and_saveexec_b64 s[46:47], s[4:5]
	s_cbranch_execz .LBB0_511
	s_waitcnt lgkmcnt(0)
	v_add_f32_e32 v99, v99, v134
	v_or_b32_e32 v134, 16, v120
	v_ashrrev_i32_e32 v135, 31, v134
	v_lshlrev_b64 v[134:135], 6, v[134:135]
	v_lshl_add_u64 v[134:135], s[18:19], 0, v[134:135]
	v_lshl_add_u64 v[134:135], s[44:45], 2, v[134:135]
	s_lshl_b32 s10, s59, 2
	v_lshl_add_u64 v[134:135], v[134:135], 0, s[10:11]
	global_store_dword v[134:135], v99, off
.LBB0_511:
	s_or_b64 exec, exec, s[46:47]
	v_cvt_pk_bf16_f32 v116, v116, v121
	v_cvt_pk_bf16_f32 v117, v117, v118
	v_cvt_pk_bf16_f32 v118, v112, v119
	v_cvt_pk_bf16_f32 v119, v114, v115
	v_cvt_pk_bf16_f32 v100, v100, v113
	v_cvt_pk_bf16_f32 v101, v101, v102
	v_cvt_pk_bf16_f32 v102, v96, v103
	v_cvt_pk_bf16_f32 v103, v97, v98
	ds_write_b128 v204, v[116:119]
	ds_write_b128 v204, v[100:103] offset:64
	ds_read_b128 v[96:99], v205
	ds_read_b128 v[100:103], v205 offset:1152
	v_add_co_u32_e32 v112, vcc, s64, v122
	s_nop 1
	v_addc_co_u32_e32 v113, vcc, 0, v123, vcc
	s_waitcnt lgkmcnt(1)
	global_store_dwordx4 v[112:113], v[96:99], off nt
	s_nop 1
	v_add_co_u32_e32 v96, vcc, s71, v122
	s_nop 1
	v_addc_co_u32_e32 v97, vcc, 0, v123, vcc
	s_waitcnt lgkmcnt(0)
	global_store_dwordx4 v[96:97], v[100:103], off nt
	s_waitcnt vmcnt(14)
	ds_write_b128 v205, v[168:171]
	ds_write_b128 v205, v[172:175] offset:1152
	ds_read_b128 v[96:99], v204
	ds_read_b128 v[100:103], v204 offset:64
	s_waitcnt lgkmcnt(1)
	v_lshlrev_b32_e32 v112, 16, v96
	v_and_b32_e32 v96, 0xffff0000, v96
	v_add_f32_e32 v96, v93, v96
	v_lshlrev_b32_e32 v93, 16, v97
	v_add_f32_e32 v93, v94, v93
	v_and_b32_e32 v94, 0xffff0000, v97
	v_add_f32_e32 v94, v95, v94
	v_lshlrev_b32_e32 v95, 16, v98
	v_add_f32_e32 v88, v88, v95
	v_and_b32_e32 v95, 0xffff0000, v98
	v_add_f32_e32 v95, v89, v95
	v_lshlrev_b32_e32 v89, 16, v99
	v_add_f32_e32 v90, v90, v89
	v_and_b32_e32 v89, 0xffff0000, v99
	v_add_f32_e32 v91, v91, v89
	s_waitcnt lgkmcnt(0)
	v_lshlrev_b32_e32 v89, 16, v100
	v_add_f32_e32 v84, v84, v89
	v_and_b32_e32 v89, 0xffff0000, v100
	v_add_f32_e32 v89, v85, v89
	v_lshlrev_b32_e32 v85, 16, v101
	v_add_f32_e32 v85, v86, v85
	v_and_b32_e32 v86, 0xffff0000, v101
	v_add_f32_e32 v86, v87, v86
	v_lshlrev_b32_e32 v87, 16, v102
	v_add_f32_e32 v80, v80, v87
	v_and_b32_e32 v87, 0xffff0000, v102
	v_add_f32_e32 v87, v81, v87
	v_lshlrev_b32_e32 v81, 16, v103
	v_add_f32_e32 v81, v82, v81
	v_and_b32_e32 v82, 0xffff0000, v103
	v_add_f32_e32 v92, v92, v112
	v_add_f32_e32 v82, v83, v82
	v_mul_f32_e32 v83, v96, v96
	v_mul_f32_e32 v97, v94, v94
	v_fmac_f32_e32 v83, v92, v92
	v_fmac_f32_e32 v97, v93, v93
	v_add_f32_e32 v83, v83, v97
	v_mul_f32_e32 v97, v95, v95
	v_mul_f32_e32 v98, v91, v91
	v_fmac_f32_e32 v97, v88, v88
	v_fmac_f32_e32 v98, v90, v90
	v_add_f32_e32 v97, v97, v98
	v_add_f32_e32 v83, v83, v97
	v_mul_f32_e32 v97, v89, v89
	v_mul_f32_e32 v98, v86, v86
	v_fmac_f32_e32 v97, v84, v84
	v_fmac_f32_e32 v98, v85, v85
	v_add_f32_e32 v97, v97, v98
	v_mul_f32_e32 v98, v87, v87
	v_mul_f32_e32 v99, v82, v82
	v_fmac_f32_e32 v98, v80, v80
	v_fmac_f32_e32 v99, v81, v81
	v_add_f32_e32 v98, v98, v99
	v_add_f32_e32 v97, v97, v98
	v_add_f32_e32 v83, v83, v97
	v_mov_b32_e32 v97, v83
	s_nop 1
	v_permlane16_swap_b32_e32 v83, v97
	s_waitcnt lgkmcnt(0)
	v_add_f32_e32 v83, v83, v97
	v_mov_b32_e32 v97, v83
	s_nop 1
	v_permlane32_swap_b32_e32 v83, v97
	s_and_saveexec_b64 s[46:47], s[4:5]
	s_cbranch_execz .LBB0_513
	v_or_b32_e32 v98, 32, v120
	v_ashrrev_i32_e32 v99, 31, v98
	v_lshlrev_b64 v[98:99], 6, v[98:99]
	v_lshl_add_u64 v[98:99], s[18:19], 0, v[98:99]
	v_lshl_add_u64 v[98:99], s[44:45], 2, v[98:99]
	s_lshl_b32 s10, s59, 2
	s_waitcnt lgkmcnt(0)
	v_add_f32_e32 v83, v83, v97
	v_lshl_add_u64 v[98:99], v[98:99], 0, s[10:11]
	global_store_dword v[98:99], v83, off
.LBB0_513:
	s_or_b64 exec, exec, s[46:47]
	v_cvt_pk_bf16_f32 v92, v92, v96
	v_cvt_pk_bf16_f32 v93, v93, v94
	v_cvt_pk_bf16_f32 v94, v88, v95
	v_cvt_pk_bf16_f32 v95, v90, v91
	v_cvt_pk_bf16_f32 v84, v84, v89
	v_cvt_pk_bf16_f32 v85, v85, v86
	v_cvt_pk_bf16_f32 v86, v80, v87
	v_cvt_pk_bf16_f32 v87, v81, v82
	ds_write_b128 v204, v[92:95]
	ds_write_b128 v204, v[84:87] offset:64
	ds_read_b128 v[80:83], v205
	ds_read_b128 v[84:87], v205 offset:1152
	v_add_co_u32_e32 v88, vcc, s56, v122
	s_nop 1
	v_addc_co_u32_e32 v89, vcc, 0, v123, vcc
	s_waitcnt lgkmcnt(1)
	global_store_dwordx4 v[88:89], v[80:83], off nt
	s_nop 1
	v_add_co_u32_e32 v80, vcc, s57, v122
	s_nop 1
	v_addc_co_u32_e32 v81, vcc, 0, v123, vcc
	s_waitcnt lgkmcnt(0)
	global_store_dwordx4 v[80:81], v[84:87], off nt
	s_waitcnt vmcnt(14)
	ds_write_b128 v205, v[160:163]
	ds_write_b128 v205, v[164:167] offset:1152
	ds_read_b128 v[80:83], v204
	ds_read_b128 v[84:87], v204 offset:64
	s_waitcnt lgkmcnt(1)
	v_lshlrev_b32_e32 v88, 16, v80
	v_and_b32_e32 v80, 0xffff0000, v80
	v_add_f32_e32 v80, v77, v80
	v_lshlrev_b32_e32 v77, 16, v81
	v_add_f32_e32 v77, v78, v77
	v_and_b32_e32 v78, 0xffff0000, v81
	v_add_f32_e32 v78, v79, v78
	v_lshlrev_b32_e32 v79, 16, v82
	v_add_f32_e32 v72, v72, v79
	v_and_b32_e32 v79, 0xffff0000, v82
	v_add_f32_e32 v79, v73, v79
	v_lshlrev_b32_e32 v73, 16, v83
	v_add_f32_e32 v74, v74, v73
	v_and_b32_e32 v73, 0xffff0000, v83
	v_add_f32_e32 v75, v75, v73
	s_waitcnt lgkmcnt(0)
	v_lshlrev_b32_e32 v73, 16, v84
	v_add_f32_e32 v68, v68, v73
	v_and_b32_e32 v73, 0xffff0000, v84
	v_add_f32_e32 v73, v69, v73
	v_lshlrev_b32_e32 v69, 16, v85
	v_add_f32_e32 v69, v70, v69
	v_and_b32_e32 v70, 0xffff0000, v85
	v_add_f32_e32 v70, v71, v70
	v_lshlrev_b32_e32 v71, 16, v86
	v_add_f32_e32 v64, v64, v71
	v_and_b32_e32 v71, 0xffff0000, v86
	v_add_f32_e32 v71, v65, v71
	v_lshlrev_b32_e32 v65, 16, v87
	v_add_f32_e32 v65, v66, v65
	v_and_b32_e32 v66, 0xffff0000, v87
	v_add_f32_e32 v76, v76, v88
	v_add_f32_e32 v66, v67, v66
	v_mul_f32_e32 v67, v80, v80
	v_mul_f32_e32 v81, v78, v78
	v_fmac_f32_e32 v67, v76, v76
	v_fmac_f32_e32 v81, v77, v77
	v_add_f32_e32 v67, v67, v81
	v_mul_f32_e32 v81, v79, v79
	v_mul_f32_e32 v82, v75, v75
	v_fmac_f32_e32 v81, v72, v72
	v_fmac_f32_e32 v82, v74, v74
	v_add_f32_e32 v81, v81, v82
	v_add_f32_e32 v67, v67, v81
	v_mul_f32_e32 v81, v73, v73
	v_mul_f32_e32 v82, v70, v70
	v_fmac_f32_e32 v81, v68, v68
	v_fmac_f32_e32 v82, v69, v69
	v_add_f32_e32 v81, v81, v82
	v_mul_f32_e32 v82, v71, v71
	v_mul_f32_e32 v83, v66, v66
	v_fmac_f32_e32 v82, v64, v64
	v_fmac_f32_e32 v83, v65, v65
	v_add_f32_e32 v82, v82, v83
	v_add_f32_e32 v81, v81, v82
	v_add_f32_e32 v67, v67, v81
	v_mov_b32_e32 v81, v67
	s_nop 1
	v_permlane16_swap_b32_e32 v67, v81
	s_waitcnt lgkmcnt(0)
	v_add_f32_e32 v67, v67, v81
	v_mov_b32_e32 v81, v67
	s_nop 1
	v_permlane32_swap_b32_e32 v67, v81
	s_and_saveexec_b64 s[46:47], s[4:5]
	s_cbranch_execz .LBB0_515
	v_or_b32_e32 v82, 48, v120
	v_ashrrev_i32_e32 v83, 31, v82
	v_lshlrev_b64 v[82:83], 6, v[82:83]
	v_lshl_add_u64 v[82:83], s[18:19], 0, v[82:83]
	v_lshl_add_u64 v[82:83], s[44:45], 2, v[82:83]
	s_lshl_b32 s10, s59, 2
	s_waitcnt lgkmcnt(0)
	v_add_f32_e32 v67, v67, v81
	v_lshl_add_u64 v[82:83], v[82:83], 0, s[10:11]
	global_store_dword v[82:83], v67, off
.LBB0_515:
	s_or_b64 exec, exec, s[46:47]
	v_cvt_pk_bf16_f32 v76, v76, v80
	v_cvt_pk_bf16_f32 v77, v77, v78
	v_cvt_pk_bf16_f32 v78, v72, v79
	v_cvt_pk_bf16_f32 v79, v74, v75
	v_cvt_pk_bf16_f32 v68, v68, v73
	v_cvt_pk_bf16_f32 v69, v69, v70
	v_cvt_pk_bf16_f32 v70, v64, v71
	v_cvt_pk_bf16_f32 v71, v65, v66
	ds_write_b128 v204, v[76:79]
	ds_write_b128 v204, v[68:71] offset:64
	ds_read_b128 v[64:67], v205
	ds_read_b128 v[68:71], v205 offset:1152
	v_add_co_u32_e32 v72, vcc, s63, v122
	s_nop 1
	v_addc_co_u32_e32 v73, vcc, 0, v123, vcc
	s_waitcnt lgkmcnt(1)
	global_store_dwordx4 v[72:73], v[64:67], off nt
	s_nop 1
	v_add_co_u32_e32 v64, vcc, s65, v122
	s_nop 1
	v_addc_co_u32_e32 v65, vcc, 0, v123, vcc
	s_waitcnt lgkmcnt(0)
	global_store_dwordx4 v[64:65], v[68:71], off nt
	s_waitcnt vmcnt(14)
	ds_write_b128 v205, v[152:155]
	ds_write_b128 v205, v[156:159] offset:1152
	ds_read_b128 v[64:67], v204
	ds_read_b128 v[68:71], v204 offset:64
	s_waitcnt lgkmcnt(1)
	v_lshlrev_b32_e32 v72, 16, v64
	v_and_b32_e32 v64, 0xffff0000, v64
	v_add_f32_e32 v64, v61, v64
	v_lshlrev_b32_e32 v61, 16, v65
	v_add_f32_e32 v61, v62, v61
	v_and_b32_e32 v62, 0xffff0000, v65
	v_add_f32_e32 v62, v63, v62
	v_lshlrev_b32_e32 v63, 16, v66
	v_add_f32_e32 v56, v56, v63
	v_and_b32_e32 v63, 0xffff0000, v66
	v_add_f32_e32 v63, v57, v63
	v_lshlrev_b32_e32 v57, 16, v67
	v_add_f32_e32 v58, v58, v57
	v_and_b32_e32 v57, 0xffff0000, v67
	v_add_f32_e32 v59, v59, v57
	s_waitcnt lgkmcnt(0)
	v_lshlrev_b32_e32 v57, 16, v68
	v_add_f32_e32 v52, v52, v57
	v_and_b32_e32 v57, 0xffff0000, v68
	v_add_f32_e32 v57, v53, v57
	v_lshlrev_b32_e32 v53, 16, v69
	v_add_f32_e32 v53, v54, v53
	v_and_b32_e32 v54, 0xffff0000, v69
	v_add_f32_e32 v54, v55, v54
	v_lshlrev_b32_e32 v55, 16, v70
	v_add_f32_e32 v48, v48, v55
	v_and_b32_e32 v55, 0xffff0000, v70
	v_add_f32_e32 v55, v49, v55
	v_lshlrev_b32_e32 v49, 16, v71
	v_add_f32_e32 v49, v50, v49
	v_and_b32_e32 v50, 0xffff0000, v71
	v_add_f32_e32 v60, v60, v72
	v_add_f32_e32 v50, v51, v50
	v_mul_f32_e32 v51, v64, v64
	v_mul_f32_e32 v65, v62, v62
	v_fmac_f32_e32 v51, v60, v60
	v_fmac_f32_e32 v65, v61, v61
	v_add_f32_e32 v51, v51, v65
	v_mul_f32_e32 v65, v63, v63
	v_mul_f32_e32 v66, v59, v59
	v_fmac_f32_e32 v65, v56, v56
	v_fmac_f32_e32 v66, v58, v58
	v_add_f32_e32 v65, v65, v66
	v_add_f32_e32 v51, v51, v65
	v_mul_f32_e32 v65, v57, v57
	v_mul_f32_e32 v66, v54, v54
	v_fmac_f32_e32 v65, v52, v52
	v_fmac_f32_e32 v66, v53, v53
	v_add_f32_e32 v65, v65, v66
	v_mul_f32_e32 v66, v55, v55
	v_mul_f32_e32 v67, v50, v50
	v_fmac_f32_e32 v66, v48, v48
	v_fmac_f32_e32 v67, v49, v49
	v_add_f32_e32 v66, v66, v67
	v_add_f32_e32 v65, v65, v66
	v_add_f32_e32 v51, v51, v65
	v_mov_b32_e32 v65, v51
	s_nop 1
	v_permlane16_swap_b32_e32 v51, v65
	s_waitcnt lgkmcnt(0)
	v_add_f32_e32 v51, v51, v65
	v_mov_b32_e32 v65, v51
	s_nop 1
	v_permlane32_swap_b32_e32 v51, v65
	s_and_saveexec_b64 s[46:47], s[4:5]
	s_cbranch_execz .LBB0_517
	v_add_u32_e32 v66, 0x80, v120
	v_ashrrev_i32_e32 v67, 31, v66
	v_lshlrev_b64 v[66:67], 6, v[66:67]
	v_lshl_add_u64 v[66:67], s[18:19], 0, v[66:67]
	v_lshl_add_u64 v[66:67], s[44:45], 2, v[66:67]
	s_lshl_b32 s10, s59, 2
	s_waitcnt lgkmcnt(0)
	v_add_f32_e32 v51, v51, v65
	v_lshl_add_u64 v[66:67], v[66:67], 0, s[10:11]
	global_store_dword v[66:67], v51, off
.LBB0_517:
	s_or_b64 exec, exec, s[46:47]
	v_cvt_pk_bf16_f32 v60, v60, v64
	v_cvt_pk_bf16_f32 v61, v61, v62
	v_cvt_pk_bf16_f32 v62, v56, v63
	v_cvt_pk_bf16_f32 v63, v58, v59
	v_cvt_pk_bf16_f32 v52, v52, v57
	v_cvt_pk_bf16_f32 v53, v53, v54
	v_cvt_pk_bf16_f32 v54, v48, v55
	v_cvt_pk_bf16_f32 v55, v49, v50
	ds_write_b128 v204, v[60:63]
	ds_write_b128 v204, v[52:55] offset:64
	ds_read_b128 v[48:51], v205
	ds_read_b128 v[52:55], v205 offset:1152
	v_add_co_u32_e32 v56, vcc, s72, v122
	s_nop 1
	v_addc_co_u32_e32 v57, vcc, 0, v123, vcc
	s_waitcnt lgkmcnt(1)
	global_store_dwordx4 v[56:57], v[48:51], off nt
	s_nop 1
	v_add_co_u32_e32 v48, vcc, s73, v122
	s_nop 1
	v_addc_co_u32_e32 v49, vcc, 0, v123, vcc
	s_waitcnt lgkmcnt(0)
	global_store_dwordx4 v[48:49], v[52:55], off nt
	s_waitcnt vmcnt(14)
	ds_write_b128 v205, v[144:147]
	ds_write_b128 v205, v[148:151] offset:1152
	ds_read_b128 v[48:51], v204
	ds_read_b128 v[52:55], v204 offset:64
	s_waitcnt lgkmcnt(1)
	v_lshlrev_b32_e32 v56, 16, v48
	v_and_b32_e32 v48, 0xffff0000, v48
	v_add_f32_e32 v48, v45, v48
	v_lshlrev_b32_e32 v45, 16, v49
	v_add_f32_e32 v45, v46, v45
	v_and_b32_e32 v46, 0xffff0000, v49
	v_add_f32_e32 v46, v47, v46
	v_lshlrev_b32_e32 v47, 16, v50
	v_add_f32_e32 v40, v40, v47
	v_and_b32_e32 v47, 0xffff0000, v50
	v_add_f32_e32 v47, v41, v47
	v_lshlrev_b32_e32 v41, 16, v51
	v_add_f32_e32 v42, v42, v41
	v_and_b32_e32 v41, 0xffff0000, v51
	v_add_f32_e32 v43, v43, v41
	s_waitcnt lgkmcnt(0)
	v_lshlrev_b32_e32 v41, 16, v52
	v_add_f32_e32 v36, v36, v41
	v_and_b32_e32 v41, 0xffff0000, v52
	v_add_f32_e32 v41, v37, v41
	v_lshlrev_b32_e32 v37, 16, v53
	v_add_f32_e32 v37, v38, v37
	v_and_b32_e32 v38, 0xffff0000, v53
	v_add_f32_e32 v38, v39, v38
	v_lshlrev_b32_e32 v39, 16, v54
	v_add_f32_e32 v32, v32, v39
	v_and_b32_e32 v39, 0xffff0000, v54
	v_add_f32_e32 v39, v33, v39
	v_lshlrev_b32_e32 v33, 16, v55
	v_add_f32_e32 v33, v34, v33
	v_and_b32_e32 v34, 0xffff0000, v55
	v_add_f32_e32 v44, v44, v56
	v_add_f32_e32 v34, v35, v34
	v_mul_f32_e32 v35, v48, v48
	v_mul_f32_e32 v49, v46, v46
	v_fmac_f32_e32 v35, v44, v44
	v_fmac_f32_e32 v49, v45, v45
	v_add_f32_e32 v35, v35, v49
	v_mul_f32_e32 v49, v47, v47
	v_mul_f32_e32 v50, v43, v43
	v_fmac_f32_e32 v49, v40, v40
	v_fmac_f32_e32 v50, v42, v42
	v_add_f32_e32 v49, v49, v50
	v_add_f32_e32 v35, v35, v49
	v_mul_f32_e32 v49, v41, v41
	v_mul_f32_e32 v50, v38, v38
	v_fmac_f32_e32 v49, v36, v36
	v_fmac_f32_e32 v50, v37, v37
	v_add_f32_e32 v49, v49, v50
	v_mul_f32_e32 v50, v39, v39
	v_mul_f32_e32 v51, v34, v34
	v_fmac_f32_e32 v50, v32, v32
	v_fmac_f32_e32 v51, v33, v33
	v_add_f32_e32 v50, v50, v51
	v_add_f32_e32 v49, v49, v50
	v_add_f32_e32 v35, v35, v49
	v_mov_b32_e32 v49, v35
	s_nop 1
	v_permlane16_swap_b32_e32 v35, v49
	s_waitcnt lgkmcnt(0)
	v_add_f32_e32 v35, v35, v49
	v_mov_b32_e32 v49, v35
	s_nop 1
	v_permlane32_swap_b32_e32 v35, v49
	s_and_saveexec_b64 s[46:47], s[4:5]
	s_cbranch_execz .LBB0_519
	v_add_u32_e32 v50, 0x90, v120
	v_ashrrev_i32_e32 v51, 31, v50
	v_lshlrev_b64 v[50:51], 6, v[50:51]
	v_lshl_add_u64 v[50:51], s[18:19], 0, v[50:51]
	v_lshl_add_u64 v[50:51], s[44:45], 2, v[50:51]
	s_lshl_b32 s10, s59, 2
	s_waitcnt lgkmcnt(0)
	v_add_f32_e32 v35, v35, v49
	v_lshl_add_u64 v[50:51], v[50:51], 0, s[10:11]
	global_store_dword v[50:51], v35, off
.LBB0_519:
	s_or_b64 exec, exec, s[46:47]
	v_cvt_pk_bf16_f32 v44, v44, v48
	v_cvt_pk_bf16_f32 v45, v45, v46
	v_cvt_pk_bf16_f32 v46, v40, v47
	v_cvt_pk_bf16_f32 v47, v42, v43
	v_cvt_pk_bf16_f32 v36, v36, v41
	v_cvt_pk_bf16_f32 v37, v37, v38
	v_cvt_pk_bf16_f32 v38, v32, v39
	v_cvt_pk_bf16_f32 v39, v33, v34
	ds_write_b128 v204, v[44:47]
	ds_write_b128 v204, v[36:39] offset:64
	ds_read_b128 v[32:35], v205
	ds_read_b128 v[36:39], v205 offset:1152
	v_add_co_u32_e32 v40, vcc, s74, v122
	s_nop 1
	v_addc_co_u32_e32 v41, vcc, 0, v123, vcc
	s_waitcnt lgkmcnt(1)
	global_store_dwordx4 v[40:41], v[32:35], off nt
	s_nop 1
	v_add_co_u32_e32 v32, vcc, s75, v122
	s_nop 1
	v_addc_co_u32_e32 v33, vcc, 0, v123, vcc
	s_waitcnt lgkmcnt(0)
	global_store_dwordx4 v[32:33], v[36:39], off nt
	s_waitcnt vmcnt(14)
	ds_write_b128 v205, v[124:127]
	ds_write_b128 v205, v[128:131] offset:1152
	ds_read_b128 v[32:35], v204
	ds_read_b128 v[36:39], v204 offset:64
	s_waitcnt lgkmcnt(1)
	v_lshlrev_b32_e32 v40, 16, v32
	v_and_b32_e32 v32, 0xffff0000, v32
	v_add_f32_e32 v32, v29, v32
	v_lshlrev_b32_e32 v29, 16, v33
	v_add_f32_e32 v29, v30, v29
	v_and_b32_e32 v30, 0xffff0000, v33
	v_add_f32_e32 v30, v31, v30
	v_lshlrev_b32_e32 v31, 16, v34
	v_add_f32_e32 v24, v24, v31
	v_and_b32_e32 v31, 0xffff0000, v34
	v_add_f32_e32 v31, v25, v31
	v_lshlrev_b32_e32 v25, 16, v35
	v_add_f32_e32 v26, v26, v25
	v_and_b32_e32 v25, 0xffff0000, v35
	v_add_f32_e32 v27, v27, v25
	s_waitcnt lgkmcnt(0)
	v_lshlrev_b32_e32 v25, 16, v36
	v_add_f32_e32 v20, v20, v25
	v_and_b32_e32 v25, 0xffff0000, v36
	v_add_f32_e32 v25, v21, v25
	v_lshlrev_b32_e32 v21, 16, v37
	v_add_f32_e32 v21, v22, v21
	v_and_b32_e32 v22, 0xffff0000, v37
	v_add_f32_e32 v22, v23, v22
	v_lshlrev_b32_e32 v23, 16, v38
	v_add_f32_e32 v16, v16, v23
	v_and_b32_e32 v23, 0xffff0000, v38
	v_add_f32_e32 v23, v17, v23
	v_lshlrev_b32_e32 v17, 16, v39
	v_add_f32_e32 v17, v18, v17
	v_and_b32_e32 v18, 0xffff0000, v39
	v_add_f32_e32 v28, v28, v40
	v_add_f32_e32 v18, v19, v18
	v_mul_f32_e32 v19, v32, v32
	v_mul_f32_e32 v33, v30, v30
	v_fmac_f32_e32 v19, v28, v28
	v_fmac_f32_e32 v33, v29, v29
	v_add_f32_e32 v19, v19, v33
	v_mul_f32_e32 v33, v31, v31
	v_mul_f32_e32 v34, v27, v27
	v_fmac_f32_e32 v33, v24, v24
	v_fmac_f32_e32 v34, v26, v26
	v_add_f32_e32 v33, v33, v34
	v_add_f32_e32 v19, v19, v33
	v_mul_f32_e32 v33, v25, v25
	v_mul_f32_e32 v34, v22, v22
	v_fmac_f32_e32 v33, v20, v20
	v_fmac_f32_e32 v34, v21, v21
	v_add_f32_e32 v33, v33, v34
	v_mul_f32_e32 v34, v23, v23
	v_mul_f32_e32 v35, v18, v18
	v_fmac_f32_e32 v34, v16, v16
	v_fmac_f32_e32 v35, v17, v17
	v_add_f32_e32 v34, v34, v35
	v_add_f32_e32 v33, v33, v34
	v_add_f32_e32 v19, v19, v33
	v_mov_b32_e32 v33, v19
	s_nop 1
	v_permlane16_swap_b32_e32 v19, v33
	s_waitcnt lgkmcnt(0)
	v_add_f32_e32 v19, v19, v33
	v_mov_b32_e32 v33, v19
	s_nop 1
	v_permlane32_swap_b32_e32 v19, v33
	s_and_saveexec_b64 s[46:47], s[4:5]
	s_cbranch_execz .LBB0_521
	v_add_u32_e32 v34, 0xa0, v120
	v_ashrrev_i32_e32 v35, 31, v34
	v_lshlrev_b64 v[34:35], 6, v[34:35]
	v_lshl_add_u64 v[34:35], s[18:19], 0, v[34:35]
	v_lshl_add_u64 v[34:35], s[44:45], 2, v[34:35]
	s_lshl_b32 s10, s59, 2
	s_waitcnt lgkmcnt(0)
	v_add_f32_e32 v19, v19, v33
	v_lshl_add_u64 v[34:35], v[34:35], 0, s[10:11]
	global_store_dword v[34:35], v19, off
.LBB0_521:
	s_or_b64 exec, exec, s[46:47]
	v_cvt_pk_bf16_f32 v28, v28, v32
	v_cvt_pk_bf16_f32 v29, v29, v30
	v_cvt_pk_bf16_f32 v30, v24, v31
	v_cvt_pk_bf16_f32 v31, v26, v27
	v_cvt_pk_bf16_f32 v20, v20, v25
	v_cvt_pk_bf16_f32 v21, v21, v22
	v_cvt_pk_bf16_f32 v22, v16, v23
	v_cvt_pk_bf16_f32 v23, v17, v18
	ds_write_b128 v204, v[28:31]
	ds_write_b128 v204, v[20:23] offset:64
	ds_read_b128 v[16:19], v205
	ds_read_b128 v[20:23], v205 offset:1152
	v_add_co_u32_e32 v24, vcc, s79, v122
	s_nop 1
	v_addc_co_u32_e32 v25, vcc, 0, v123, vcc
	s_waitcnt lgkmcnt(1)
	global_store_dwordx4 v[24:25], v[16:19], off nt
	s_nop 1
	v_add_co_u32_e32 v16, vcc, s80, v122
	s_nop 1
	v_addc_co_u32_e32 v17, vcc, 0, v123, vcc
	s_waitcnt lgkmcnt(0)
	global_store_dwordx4 v[16:17], v[20:23], off nt
	s_waitcnt vmcnt(14)
	ds_write_b128 v205, v[104:107]
	ds_write_b128 v205, v[108:111] offset:1152
	ds_read_b128 v[16:19], v204
	ds_read_b128 v[20:23], v204 offset:64
	s_waitcnt lgkmcnt(1)
	v_lshlrev_b32_e32 v24, 16, v16
	v_and_b32_e32 v16, 0xffff0000, v16
	v_add_f32_e32 v16, v13, v16
	v_lshlrev_b32_e32 v13, 16, v17
	v_add_f32_e32 v13, v14, v13
	v_and_b32_e32 v14, 0xffff0000, v17
	v_add_f32_e32 v14, v15, v14
	v_lshlrev_b32_e32 v15, 16, v18
	v_add_f32_e32 v8, v8, v15
	v_and_b32_e32 v15, 0xffff0000, v18
	v_add_f32_e32 v15, v9, v15
	v_lshlrev_b32_e32 v9, 16, v19
	v_add_f32_e32 v10, v10, v9
	v_and_b32_e32 v9, 0xffff0000, v19
	v_add_f32_e32 v11, v11, v9
	s_waitcnt lgkmcnt(0)
	v_lshlrev_b32_e32 v9, 16, v20
	v_add_f32_e32 v4, v4, v9
	v_and_b32_e32 v9, 0xffff0000, v20
	v_add_f32_e32 v9, v5, v9
	v_lshlrev_b32_e32 v5, 16, v21
	v_add_f32_e32 v5, v6, v5
	v_and_b32_e32 v6, 0xffff0000, v21
	v_add_f32_e32 v6, v7, v6
	v_lshlrev_b32_e32 v7, 16, v22
	v_add_f32_e32 v0, v0, v7
	v_and_b32_e32 v7, 0xffff0000, v22
	v_add_f32_e32 v7, v1, v7
	v_lshlrev_b32_e32 v1, 16, v23
	v_add_f32_e32 v1, v2, v1
	v_and_b32_e32 v2, 0xffff0000, v23
	v_add_f32_e32 v12, v12, v24
	v_add_f32_e32 v2, v3, v2
	v_mul_f32_e32 v3, v16, v16
	v_mul_f32_e32 v17, v14, v14
	v_fmac_f32_e32 v3, v12, v12
	v_fmac_f32_e32 v17, v13, v13
	v_add_f32_e32 v3, v3, v17
	v_mul_f32_e32 v17, v15, v15
	v_mul_f32_e32 v18, v11, v11
	v_fmac_f32_e32 v17, v8, v8
	v_fmac_f32_e32 v18, v10, v10
	v_add_f32_e32 v17, v17, v18
	v_add_f32_e32 v3, v3, v17
	v_mul_f32_e32 v17, v9, v9
	v_mul_f32_e32 v18, v6, v6
	v_fmac_f32_e32 v17, v4, v4
	v_fmac_f32_e32 v18, v5, v5
	v_add_f32_e32 v17, v17, v18
	v_mul_f32_e32 v18, v7, v7
	v_mul_f32_e32 v19, v2, v2
	v_fmac_f32_e32 v18, v0, v0
	v_fmac_f32_e32 v19, v1, v1
	v_add_f32_e32 v18, v18, v19
	v_add_f32_e32 v17, v17, v18
	v_add_f32_e32 v3, v3, v17
	v_mov_b32_e32 v17, v3
	s_nop 1
	v_permlane16_swap_b32_e32 v3, v17
	s_waitcnt lgkmcnt(0)
	v_add_f32_e32 v3, v3, v17
	v_mov_b32_e32 v17, v3
	s_nop 1
	v_permlane32_swap_b32_e32 v3, v17
	s_and_saveexec_b64 s[46:47], s[4:5]
	s_cbranch_execz .LBB0_523
	v_add_u32_e32 v18, 0xb0, v120
	v_ashrrev_i32_e32 v19, 31, v18
	v_lshlrev_b64 v[18:19], 6, v[18:19]
	v_lshl_add_u64 v[18:19], s[18:19], 0, v[18:19]
	v_lshl_add_u64 v[18:19], s[44:45], 2, v[18:19]
	s_lshl_b32 s10, s59, 2
	s_waitcnt lgkmcnt(0)
	v_add_f32_e32 v3, v3, v17
	v_lshl_add_u64 v[18:19], v[18:19], 0, s[10:11]
	global_store_dword v[18:19], v3, off
